# v25
# speedup vs baseline: 1.0322x; 1.0138x over previous
; __device__ __forceinline__ int crow(int r, int hi) { return (r & 3) + 8 * (r >> 2) + 4 * hi; }
; __device__ __forceinline__ unsigned cvtpk(float lo, float hi) { return pg8::cvt_pk_bf16(lo, hi); }
; __device__ __forceinline__ float bf2f(unsigned b) { return __uint_as_float(b << 16); }
; __device__ __forceinline__ void sb_block(const att::bf16* Qh, const att::bf16* Kh, const att::bf16* Vh, const bf16_t* Zs, bf16_t* UB, int head, int P0, char* lds) {
;     ...
; #pragma unroll
;     for (int r = 0; r < 16; ++r) { const int orow = qlo + crow(r, hi);
; #pragma unroll
;         for (int d0 = 0; d0 < 4; ++d0) { const float v = o[d0][r]; const float vn = __shfl_xor(v, 1);
;             if ((r32 & 1) == 0) { const size_t off = (size_t)orow * DM + head * 128 + d0 * 32 + r32; const unsigned zz = *(const unsigned*)(Zs + off);
;                 *(unsigned*)(UB + (size_t)orow * (2 * DM) + DM + head * 128 + d0 * 32 + r32) = cvtpk(v * bf2f(zz & 0xffffu), vn * bf2f(zz >> 16)); } } }
.LBB0_368:
	v_xor_b32_e32 v65, 1, v234
	v_cmp_lt_i32_e32 vcc, v65, v72
	v_or_b32_e32 v64, s22, v186
	s_lshl_b32 s22, s44, 8
	v_cndmask_b32_e32 v65, v234, v65, vcc
	v_lshlrev_b32_e32 v74, 2, v65
	v_and_b32_e32 v65, 1, v183
	s_add_u32 s8, s24, s22
	v_cmp_eq_u32_e32 vcc, 0, v65
	s_addc_u32 s9, s25, 0
	v_lshlrev_b32_e32 v200, 1, v182
	v_ashrrev_i32_e32 v65, 31, v64
	v_lshl_add_u64 v[66:67], s[8:9], 0, v[200:201]
	v_lshlrev_b64 v[68:69], 12, v[64:65]
	v_lshl_add_u64 v[70:71], v[66:67], 0, v[68:69]
	v_lshlrev_b64 v[68:69], 13, v[64:65]
	ds_bpermute_b32 v73, v74, v48
	v_lshl_add_u64 v[68:69], s[6:7], 0, v[68:69]
	v_lshl_add_u64 v[68:69], v[68:69], 0, s[22:23]
	v_lshl_add_u64 v[68:69], v[68:69], 0, v[200:201]
	v_lshl_add_u64 v[68:69], v[68:69], 0, s[36:37]
	s_waitcnt vmcnt(0)
	s_mov_b64 s[98:99], 0x1000
	s_mov_b64 s[100:101], 0x5000
	v_mov_b64_e32 v[244:245], v[70:71]
	s_and_saveexec_b64 s[8:9], vcc
	global_load_dword v112, v[244:245], off
	global_load_dword v113, v[244:245], off offset:64
	global_load_dword v114, v[244:245], off offset:128
	global_load_dword v115, v[244:245], off offset:192
	v_lshl_add_u64 v[244:245], v[244:245], 0, s[98:99]
	global_load_dword v116, v[244:245], off
	global_load_dword v117, v[244:245], off offset:64
	global_load_dword v118, v[244:245], off offset:128
	global_load_dword v119, v[244:245], off offset:192
	v_lshl_add_u64 v[244:245], v[244:245], 0, s[98:99]
	global_load_dword v120, v[244:245], off
	global_load_dword v121, v[244:245], off offset:64
	global_load_dword v122, v[244:245], off offset:128
	global_load_dword v123, v[244:245], off offset:192
	v_lshl_add_u64 v[244:245], v[244:245], 0, s[98:99]
	global_load_dword v124, v[244:245], off
	global_load_dword v125, v[244:245], off offset:64
	global_load_dword v126, v[244:245], off offset:128
	global_load_dword v127, v[244:245], off offset:192
	v_lshl_add_u64 v[244:245], v[244:245], 0, s[100:101]
	global_load_dword v128, v[244:245], off
	global_load_dword v129, v[244:245], off offset:64
	global_load_dword v130, v[244:245], off offset:128
	global_load_dword v131, v[244:245], off offset:192
	v_lshl_add_u64 v[244:245], v[244:245], 0, s[98:99]
	global_load_dword v132, v[244:245], off
	global_load_dword v133, v[244:245], off offset:64
	global_load_dword v134, v[244:245], off offset:128
	global_load_dword v135, v[244:245], off offset:192
	v_lshl_add_u64 v[244:245], v[244:245], 0, s[98:99]
	global_load_dword v136, v[244:245], off
	global_load_dword v137, v[244:245], off offset:64
	global_load_dword v138, v[244:245], off offset:128
	global_load_dword v139, v[244:245], off offset:192
	v_lshl_add_u64 v[244:245], v[244:245], 0, s[98:99]
	global_load_dword v140, v[244:245], off
	global_load_dword v141, v[244:245], off offset:64
	global_load_dword v142, v[244:245], off offset:128
	global_load_dword v143, v[244:245], off offset:192
	v_lshl_add_u64 v[244:245], v[244:245], 0, s[100:101]
	global_load_dword v144, v[244:245], off
	global_load_dword v145, v[244:245], off offset:64
	global_load_dword v146, v[244:245], off offset:128
	global_load_dword v147, v[244:245], off offset:192
	v_lshl_add_u64 v[244:245], v[244:245], 0, s[98:99]
	global_load_dword v148, v[244:245], off
	global_load_dword v149, v[244:245], off offset:64
	global_load_dword v150, v[244:245], off offset:128
	global_load_dword v151, v[244:245], off offset:192
	v_lshl_add_u64 v[244:245], v[244:245], 0, s[98:99]
	global_load_dword v152, v[244:245], off
	global_load_dword v153, v[244:245], off offset:64
	global_load_dword v154, v[244:245], off offset:128
	global_load_dword v155, v[244:245], off offset:192
	v_lshl_add_u64 v[244:245], v[244:245], 0, s[98:99]
	global_load_dword v156, v[244:245], off
	global_load_dword v157, v[244:245], off offset:64
	global_load_dword v158, v[244:245], off offset:128
	global_load_dword v159, v[244:245], off offset:192
	v_lshl_add_u64 v[244:245], v[244:245], 0, s[100:101]
	global_load_dword v160, v[244:245], off
	global_load_dword v161, v[244:245], off offset:64
	global_load_dword v162, v[244:245], off offset:128
	global_load_dword v163, v[244:245], off offset:192
	v_lshl_add_u64 v[244:245], v[244:245], 0, s[98:99]
	global_load_dword v164, v[244:245], off
	global_load_dword v165, v[244:245], off offset:64
	global_load_dword v166, v[244:245], off offset:128
	global_load_dword v167, v[244:245], off offset:192
	v_lshl_add_u64 v[244:245], v[244:245], 0, s[98:99]
	global_load_dword v168, v[244:245], off
	global_load_dword v169, v[244:245], off offset:64
	global_load_dword v170, v[244:245], off offset:128
	global_load_dword v171, v[244:245], off offset:192
	v_lshl_add_u64 v[244:245], v[244:245], 0, s[98:99]
	global_load_dword v172, v[244:245], off
	global_load_dword v173, v[244:245], off offset:64
	global_load_dword v174, v[244:245], off offset:128
	global_load_dword v175, v[244:245], off offset:192
	s_or_b64 exec, exec, s[8:9]
	s_and_saveexec_b64 s[8:9], vcc
	s_cbranch_execz .LBB0_370
	v_mov_b32_e32 v72, v48
	s_waitcnt vmcnt(63)
	v_lshlrev_b32_e32 v76, 16, v112
	v_and_b32_e32 v77, 0xffff0000, v112
	s_waitcnt lgkmcnt(0)
	v_pk_mul_f32 v[72:73], v[72:73], v[76:77]
	s_nop 0
	v_cvt_pk_bf16_f32 v48, v72, v73
	global_store_dword v[68:69], v48, off
.LBB0_370:
	s_or_b64 exec, exec, s[8:9]
	s_waitcnt lgkmcnt(0)
	ds_bpermute_b32 v73, v74, v32
	s_and_saveexec_b64 s[8:9], vcc
	s_cbranch_execz .LBB0_372
	v_mov_b32_e32 v72, v32
	s_waitcnt vmcnt(63)
	v_lshlrev_b32_e32 v76, 16, v113
	v_and_b32_e32 v77, 0xffff0000, v113
	s_waitcnt lgkmcnt(0)
	v_pk_mul_f32 v[72:73], v[72:73], v[76:77]
	s_nop 0
	v_cvt_pk_bf16_f32 v32, v72, v73
	global_store_dword v[68:69], v32, off offset:64
; __device__ __forceinline__ int crow(int r, int hi) { return (r & 3) + 8 * (r >> 2) + 4 * hi; }
; __device__ __forceinline__ unsigned cvtpk(float lo, float hi) { return pg8::cvt_pk_bf16(lo, hi); }
; __device__ __forceinline__ float bf2f(unsigned b) { return __uint_as_float(b << 16); }
; __device__ __forceinline__ void sb_block(const att::bf16* Qh, const att::bf16* Kh, const att::bf16* Vh, const bf16_t* Zs, bf16_t* UB, int head, int P0, char* lds) {
;     ...
; #pragma unroll
;     for (int r = 0; r < 16; ++r) { const int orow = qlo + crow(r, hi);
; #pragma unroll
;         for (int d0 = 0; d0 < 4; ++d0) { const float v = o[d0][r]; const float vn = __shfl_xor(v, 1);
;             if ((r32 & 1) == 0) { const size_t off = (size_t)orow * DM + head * 128 + d0 * 32 + r32; const unsigned zz = *(const unsigned*)(Zs + off);
;                 *(unsigned*)(UB + (size_t)orow * (2 * DM) + DM + head * 128 + d0 * 32 + r32) = cvtpk(v * bf2f(zz & 0xffffu), vn * bf2f(zz >> 16)); } } }
.LBB0_372:
	s_or_b64 exec, exec, s[8:9]
	s_waitcnt lgkmcnt(0)
	ds_bpermute_b32 v73, v74, v16
	s_and_saveexec_b64 s[8:9], vcc
	s_cbranch_execz .LBB0_374
	v_mov_b32_e32 v72, v16
	s_waitcnt vmcnt(63)
	v_lshlrev_b32_e32 v76, 16, v114
	v_and_b32_e32 v77, 0xffff0000, v114
	s_waitcnt lgkmcnt(0)
	v_pk_mul_f32 v[72:73], v[72:73], v[76:77]
	s_nop 0
	v_cvt_pk_bf16_f32 v16, v72, v73
	global_store_dword v[68:69], v16, off offset:128
.LBB0_374:
	s_or_b64 exec, exec, s[8:9]
	s_waitcnt lgkmcnt(0)
	ds_bpermute_b32 v73, v74, v0
	s_and_saveexec_b64 s[8:9], vcc
	s_cbranch_execz .LBB0_376
	v_mov_b32_e32 v72, v0
	s_waitcnt vmcnt(63)
	v_lshlrev_b32_e32 v70, 16, v115
	v_and_b32_e32 v71, 0xffff0000, v115
	s_waitcnt lgkmcnt(0)
	v_pk_mul_f32 v[70:71], v[72:73], v[70:71]
	s_nop 0
	v_cvt_pk_bf16_f32 v0, v70, v71
	global_store_dword v[68:69], v0, off offset:192
.LBB0_376:
	s_or_b64 exec, exec, s[8:9]
	v_or_b32_e32 v68, 1, v64
	v_ashrrev_i32_e32 v69, 31, v68
	s_lshl_b32 s8, s44, 7
	v_lshlrev_b64 v[70:71], 12, v[68:69]
	v_lshlrev_b64 v[68:69], 13, v[68:69]
	s_waitcnt lgkmcnt(0)
	ds_bpermute_b32 v73, v74, v49
	v_lshl_add_u64 v[68:69], s[6:7], 0, v[68:69]
	s_lshl_b32 s22, s8, 1
	v_lshl_add_u64 v[68:69], v[68:69], 0, s[22:23]
	v_lshl_add_u64 v[68:69], v[68:69], 0, v[200:201]
	v_lshl_add_u64 v[70:71], v[66:67], 0, v[70:71]
	v_lshl_add_u64 v[68:69], v[68:69], 0, s[36:37]
	s_and_saveexec_b64 s[8:9], vcc
	s_cbranch_execz .LBB0_378
	v_mov_b32_e32 v72, v49
	s_waitcnt vmcnt(63)
	v_lshlrev_b32_e32 v76, 16, v116
	v_and_b32_e32 v77, 0xffff0000, v116
	s_waitcnt lgkmcnt(0)
	v_pk_mul_f32 v[48:49], v[72:73], v[76:77]
	s_nop 0
	v_cvt_pk_bf16_f32 v0, v48, v49
	global_store_dword v[68:69], v0, off
.LBB0_378:
	s_or_b64 exec, exec, s[8:9]
	ds_bpermute_b32 v49, v74, v33
	s_and_saveexec_b64 s[8:9], vcc
	s_cbranch_execz .LBB0_380
	v_mov_b32_e32 v48, v33
	s_waitcnt vmcnt(63)
	v_lshlrev_b32_e32 v72, 16, v117
	s_waitcnt lgkmcnt(1)
	v_and_b32_e32 v73, 0xffff0000, v117
	s_waitcnt lgkmcnt(0)
	v_pk_mul_f32 v[32:33], v[48:49], v[72:73]
	s_nop 0
	v_cvt_pk_bf16_f32 v0, v32, v33
	global_store_dword v[68:69], v0, off offset:64
.LBB0_380:
	s_or_b64 exec, exec, s[8:9]
	ds_bpermute_b32 v33, v74, v17
	s_and_saveexec_b64 s[8:9], vcc
	s_cbranch_execz .LBB0_382
	v_mov_b32_e32 v32, v17
	s_waitcnt vmcnt(63)
	v_lshlrev_b32_e32 v48, 16, v118
	s_waitcnt lgkmcnt(1)
	v_and_b32_e32 v49, 0xffff0000, v118
	s_waitcnt lgkmcnt(0)
	v_pk_mul_f32 v[16:17], v[32:33], v[48:49]
	s_nop 0
	v_cvt_pk_bf16_f32 v0, v16, v17
	global_store_dword v[68:69], v0, off offset:128
.LBB0_382:
	s_or_b64 exec, exec, s[8:9]
	ds_bpermute_b32 v17, v74, v1
	s_and_saveexec_b64 s[8:9], vcc
	s_cbranch_execz .LBB0_384
	v_mov_b32_e32 v16, v1
	s_waitcnt vmcnt(63)
	v_lshlrev_b32_e32 v32, 16, v119
	s_waitcnt lgkmcnt(1)
	v_and_b32_e32 v33, 0xffff0000, v119
	s_waitcnt lgkmcnt(0)
	v_pk_mul_f32 v[0:1], v[16:17], v[32:33]
	s_nop 0
	v_cvt_pk_bf16_f32 v0, v0, v1
	global_store_dword v[68:69], v0, off offset:192
.LBB0_384:
	s_or_b64 exec, exec, s[8:9]
	v_or_b32_e32 v0, 2, v64
	v_ashrrev_i32_e32 v1, 31, v0
	s_waitcnt lgkmcnt(0)
	v_lshlrev_b64 v[16:17], 12, v[0:1]
	v_lshlrev_b64 v[0:1], 13, v[0:1]
	ds_bpermute_b32 v33, v74, v50
	v_lshl_add_u64 v[0:1], s[6:7], 0, v[0:1]
	v_lshl_add_u64 v[0:1], v[0:1], 0, s[22:23]
	v_lshl_add_u64 v[0:1], v[0:1], 0, v[200:201]
	v_lshl_add_u64 v[16:17], v[66:67], 0, v[16:17]
	v_lshl_add_u64 v[0:1], v[0:1], 0, s[36:37]
	s_and_saveexec_b64 s[8:9], vcc
	s_cbranch_execz .LBB0_386
	s_waitcnt vmcnt(63)
	v_lshlrev_b32_e32 v48, 16, v120
	v_and_b32_e32 v49, 0xffff0000, v120
	v_mov_b32_e32 v32, v50
	s_waitcnt lgkmcnt(0)
	v_pk_mul_f32 v[32:33], v[32:33], v[48:49]
	s_nop 0
	v_cvt_pk_bf16_f32 v32, v32, v33
	global_store_dword v[0:1], v32, off
.LBB0_386:
	s_or_b64 exec, exec, s[8:9]
	s_waitcnt lgkmcnt(0)
	ds_bpermute_b32 v33, v74, v34
	s_and_saveexec_b64 s[8:9], vcc
	s_cbranch_execz .LBB0_388
	s_waitcnt vmcnt(63)
	v_lshlrev_b32_e32 v48, 16, v121
	v_and_b32_e32 v49, 0xffff0000, v121
	v_mov_b32_e32 v32, v34
	s_waitcnt lgkmcnt(0)
	v_pk_mul_f32 v[32:33], v[32:33], v[48:49]
	s_nop 0
	v_cvt_pk_bf16_f32 v32, v32, v33
	global_store_dword v[0:1], v32, off offset:64
.LBB0_388:
	s_or_b64 exec, exec, s[8:9]
	s_waitcnt lgkmcnt(0)
	ds_bpermute_b32 v33, v74, v18
	s_and_saveexec_b64 s[8:9], vcc
	s_cbranch_execz .LBB0_390
	s_waitcnt vmcnt(63)
	v_lshlrev_b32_e32 v48, 16, v122
	v_and_b32_e32 v49, 0xffff0000, v122
	v_mov_b32_e32 v32, v18
	s_waitcnt lgkmcnt(0)
	v_pk_mul_f32 v[32:33], v[32:33], v[48:49]
	s_nop 0
	v_cvt_pk_bf16_f32 v18, v32, v33
	global_store_dword v[0:1], v18, off offset:128
.LBB0_390:
	s_or_b64 exec, exec, s[8:9]
	s_waitcnt lgkmcnt(0)
	ds_bpermute_b32 v33, v74, v2
	s_and_saveexec_b64 s[8:9], vcc
	s_cbranch_execz .LBB0_392
	v_mov_b32_e32 v32, v2
	s_waitcnt vmcnt(63)
	v_lshlrev_b32_e32 v16, 16, v123
	v_and_b32_e32 v17, 0xffff0000, v123
	s_waitcnt lgkmcnt(0)
	v_pk_mul_f32 v[16:17], v[32:33], v[16:17]
	s_nop 0
	v_cvt_pk_bf16_f32 v2, v16, v17
	global_store_dword v[0:1], v2, off offset:192
.LBB0_392:
	s_or_b64 exec, exec, s[8:9]
	v_or_b32_e32 v0, 3, v64
	v_ashrrev_i32_e32 v1, 31, v0
	v_lshlrev_b64 v[16:17], 12, v[0:1]
	v_lshlrev_b64 v[0:1], 13, v[0:1]
	s_waitcnt lgkmcnt(0)
	ds_bpermute_b32 v33, v74, v51
	v_lshl_add_u64 v[0:1], s[6:7], 0, v[0:1]
	v_lshl_add_u64 v[0:1], v[0:1], 0, s[22:23]
	v_lshl_add_u64 v[0:1], v[0:1], 0, v[200:201]
	v_lshl_add_u64 v[16:17], v[66:67], 0, v[16:17]
	v_lshl_add_u64 v[0:1], v[0:1], 0, s[36:37]
	s_and_saveexec_b64 s[8:9], vcc
	s_cbranch_execz .LBB0_394
	v_mov_b32_e32 v32, v51
	s_waitcnt vmcnt(63)
	v_lshlrev_b32_e32 v48, 16, v124
	v_and_b32_e32 v49, 0xffff0000, v124
	s_waitcnt lgkmcnt(0)
	v_pk_mul_f32 v[32:33], v[32:33], v[48:49]
	s_nop 0
	v_cvt_pk_bf16_f32 v2, v32, v33
	global_store_dword v[0:1], v2, off
; __device__ __forceinline__ int crow(int r, int hi) { return (r & 3) + 8 * (r >> 2) + 4 * hi; }
; __device__ __forceinline__ unsigned cvtpk(float lo, float hi) { return pg8::cvt_pk_bf16(lo, hi); }
; __device__ __forceinline__ float bf2f(unsigned b) { return __uint_as_float(b << 16); }
; __device__ __forceinline__ void sb_block(const att::bf16* Qh, const att::bf16* Kh, const att::bf16* Vh, const bf16_t* Zs, bf16_t* UB, int head, int P0, char* lds) {
;     ...
; #pragma unroll
;     for (int r = 0; r < 16; ++r) { const int orow = qlo + crow(r, hi);
; #pragma unroll
;         for (int d0 = 0; d0 < 4; ++d0) { const float v = o[d0][r]; const float vn = __shfl_xor(v, 1);
;             if ((r32 & 1) == 0) { const size_t off = (size_t)orow * DM + head * 128 + d0 * 32 + r32; const unsigned zz = *(const unsigned*)(Zs + off);
;                 *(unsigned*)(UB + (size_t)orow * (2 * DM) + DM + head * 128 + d0 * 32 + r32) = cvtpk(v * bf2f(zz & 0xffffu), vn * bf2f(zz >> 16)); } } }
.LBB0_394:
	s_or_b64 exec, exec, s[8:9]
	s_waitcnt lgkmcnt(0)
	ds_bpermute_b32 v33, v74, v35
	s_and_saveexec_b64 s[8:9], vcc
	s_cbranch_execz .LBB0_396
	v_mov_b32_e32 v32, v35
	s_waitcnt vmcnt(63)
	v_lshlrev_b32_e32 v48, 16, v125
	v_and_b32_e32 v49, 0xffff0000, v125
	s_waitcnt lgkmcnt(0)
	v_pk_mul_f32 v[32:33], v[32:33], v[48:49]
	s_nop 0
	v_cvt_pk_bf16_f32 v2, v32, v33
	global_store_dword v[0:1], v2, off offset:64
.LBB0_396:
	s_or_b64 exec, exec, s[8:9]
	s_waitcnt lgkmcnt(0)
	ds_bpermute_b32 v33, v74, v19
	s_and_saveexec_b64 s[8:9], vcc
	s_cbranch_execz .LBB0_398
	v_mov_b32_e32 v32, v19
	s_waitcnt vmcnt(63)
	v_lshlrev_b32_e32 v34, 16, v126
	v_and_b32_e32 v35, 0xffff0000, v126
	s_waitcnt lgkmcnt(0)
	v_pk_mul_f32 v[18:19], v[32:33], v[34:35]
	s_nop 0
	v_cvt_pk_bf16_f32 v2, v18, v19
	global_store_dword v[0:1], v2, off offset:128
.LBB0_398:
	s_or_b64 exec, exec, s[8:9]
	ds_bpermute_b32 v19, v74, v3
	s_and_saveexec_b64 s[8:9], vcc
	s_cbranch_execz .LBB0_400
	v_mov_b32_e32 v18, v3
	s_waitcnt vmcnt(63)
	v_lshlrev_b32_e32 v16, 16, v127
	v_and_b32_e32 v17, 0xffff0000, v127
	s_waitcnt lgkmcnt(0)
	v_pk_mul_f32 v[2:3], v[18:19], v[16:17]
	s_nop 0
	v_cvt_pk_bf16_f32 v2, v2, v3
	global_store_dword v[0:1], v2, off offset:192
.LBB0_400:
	s_or_b64 exec, exec, s[8:9]
	v_or_b32_e32 v0, 8, v64
	v_ashrrev_i32_e32 v1, 31, v0
	v_lshlrev_b64 v[2:3], 12, v[0:1]
	v_lshlrev_b64 v[0:1], 13, v[0:1]
	ds_bpermute_b32 v17, v74, v52
	v_lshl_add_u64 v[0:1], s[6:7], 0, v[0:1]
	v_lshl_add_u64 v[0:1], v[0:1], 0, s[22:23]
	v_lshl_add_u64 v[0:1], v[0:1], 0, v[200:201]
	v_lshl_add_u64 v[2:3], v[66:67], 0, v[2:3]
	v_lshl_add_u64 v[0:1], v[0:1], 0, s[36:37]
	s_and_saveexec_b64 s[8:9], vcc
	s_cbranch_execz .LBB0_402
	s_waitcnt vmcnt(63)
	v_lshlrev_b32_e32 v18, 16, v128
	s_waitcnt lgkmcnt(1)
	v_and_b32_e32 v19, 0xffff0000, v128
	v_mov_b32_e32 v16, v52
	s_waitcnt lgkmcnt(0)
	v_pk_mul_f32 v[16:17], v[16:17], v[18:19]
	s_nop 0
	v_cvt_pk_bf16_f32 v16, v16, v17
	global_store_dword v[0:1], v16, off
.LBB0_402:
	s_or_b64 exec, exec, s[8:9]
	s_waitcnt lgkmcnt(0)
	ds_bpermute_b32 v17, v74, v36
	s_and_saveexec_b64 s[8:9], vcc
	s_cbranch_execz .LBB0_404
	s_waitcnt vmcnt(63)
	v_lshlrev_b32_e32 v18, 16, v129
	v_and_b32_e32 v19, 0xffff0000, v129
	v_mov_b32_e32 v16, v36
	s_waitcnt lgkmcnt(0)
	v_pk_mul_f32 v[16:17], v[16:17], v[18:19]
	s_nop 0
	v_cvt_pk_bf16_f32 v16, v16, v17
	global_store_dword v[0:1], v16, off offset:64
.LBB0_404:
	s_or_b64 exec, exec, s[8:9]
	s_waitcnt lgkmcnt(0)
	ds_bpermute_b32 v17, v74, v20
	s_and_saveexec_b64 s[8:9], vcc
	s_cbranch_execz .LBB0_406
	s_waitcnt vmcnt(63)
	v_lshlrev_b32_e32 v18, 16, v130
	v_and_b32_e32 v19, 0xffff0000, v130
	v_mov_b32_e32 v16, v20
	s_waitcnt lgkmcnt(0)
	v_pk_mul_f32 v[16:17], v[16:17], v[18:19]
	s_nop 0
	v_cvt_pk_bf16_f32 v16, v16, v17
	global_store_dword v[0:1], v16, off offset:128
.LBB0_406:
	s_or_b64 exec, exec, s[8:9]
	s_waitcnt lgkmcnt(0)
	ds_bpermute_b32 v17, v74, v4
	s_and_saveexec_b64 s[8:9], vcc
	s_cbranch_execz .LBB0_408
	v_mov_b32_e32 v16, v4
	s_waitcnt vmcnt(63)
	v_lshlrev_b32_e32 v2, 16, v131
	v_and_b32_e32 v3, 0xffff0000, v131
	s_waitcnt lgkmcnt(0)
	v_pk_mul_f32 v[2:3], v[16:17], v[2:3]
	s_nop 0
	v_cvt_pk_bf16_f32 v2, v2, v3
	global_store_dword v[0:1], v2, off offset:192
.LBB0_408:
	s_or_b64 exec, exec, s[8:9]
	v_or_b32_e32 v0, 9, v64
	v_ashrrev_i32_e32 v1, 31, v0
	v_lshlrev_b64 v[2:3], 12, v[0:1]
	v_lshlrev_b64 v[0:1], 13, v[0:1]
	s_waitcnt lgkmcnt(0)
	ds_bpermute_b32 v17, v74, v53
	v_lshl_add_u64 v[0:1], s[6:7], 0, v[0:1]
	v_lshl_add_u64 v[0:1], v[0:1], 0, s[22:23]
	v_lshl_add_u64 v[0:1], v[0:1], 0, v[200:201]
	v_lshl_add_u64 v[2:3], v[66:67], 0, v[2:3]
	v_lshl_add_u64 v[0:1], v[0:1], 0, s[36:37]
	s_and_saveexec_b64 s[8:9], vcc
	s_cbranch_execz .LBB0_410
	v_mov_b32_e32 v16, v53
	s_waitcnt vmcnt(63)
	v_lshlrev_b32_e32 v18, 16, v132
	v_and_b32_e32 v19, 0xffff0000, v132
	s_waitcnt lgkmcnt(0)
	v_pk_mul_f32 v[16:17], v[16:17], v[18:19]
	s_nop 0
	v_cvt_pk_bf16_f32 v4, v16, v17
	global_store_dword v[0:1], v4, off
.LBB0_410:
	s_or_b64 exec, exec, s[8:9]
	s_waitcnt lgkmcnt(0)
	ds_bpermute_b32 v17, v74, v37
	s_and_saveexec_b64 s[8:9], vcc
	s_cbranch_execz .LBB0_412
	v_mov_b32_e32 v16, v37
	s_waitcnt vmcnt(63)
	v_lshlrev_b32_e32 v18, 16, v133
	v_and_b32_e32 v19, 0xffff0000, v133
	s_waitcnt lgkmcnt(0)
	v_pk_mul_f32 v[16:17], v[16:17], v[18:19]
	s_nop 0
	v_cvt_pk_bf16_f32 v4, v16, v17
	global_store_dword v[0:1], v4, off offset:64
.LBB0_412:
	s_or_b64 exec, exec, s[8:9]
	s_waitcnt lgkmcnt(0)
	ds_bpermute_b32 v17, v74, v21
	s_and_saveexec_b64 s[8:9], vcc
	s_cbranch_execz .LBB0_414
	v_mov_b32_e32 v16, v21
	s_waitcnt vmcnt(63)
	v_lshlrev_b32_e32 v18, 16, v134
	v_and_b32_e32 v19, 0xffff0000, v134
	s_waitcnt lgkmcnt(0)
	v_pk_mul_f32 v[16:17], v[16:17], v[18:19]
	s_nop 0
	v_cvt_pk_bf16_f32 v4, v16, v17
	global_store_dword v[0:1], v4, off offset:128
.LBB0_414:
	s_or_b64 exec, exec, s[8:9]
	s_waitcnt lgkmcnt(0)
	ds_bpermute_b32 v17, v74, v5
	s_and_saveexec_b64 s[8:9], vcc
	s_cbranch_execz .LBB0_416
	v_mov_b32_e32 v16, v5
	s_waitcnt vmcnt(63)
	v_lshlrev_b32_e32 v2, 16, v135
	v_and_b32_e32 v3, 0xffff0000, v135
	s_waitcnt lgkmcnt(0)
	v_pk_mul_f32 v[2:3], v[16:17], v[2:3]
	s_nop 0
	v_cvt_pk_bf16_f32 v2, v2, v3
	global_store_dword v[0:1], v2, off offset:192
.LBB0_416:
	s_or_b64 exec, exec, s[8:9]
	v_or_b32_e32 v0, 10, v64
	v_ashrrev_i32_e32 v1, 31, v0
	v_lshlrev_b64 v[2:3], 12, v[0:1]
	v_lshlrev_b64 v[0:1], 13, v[0:1]
	ds_bpermute_b32 v5, v74, v54
	v_lshl_add_u64 v[0:1], s[6:7], 0, v[0:1]
	v_lshl_add_u64 v[0:1], v[0:1], 0, s[22:23]
	v_lshl_add_u64 v[0:1], v[0:1], 0, v[200:201]
	v_lshl_add_u64 v[2:3], v[66:67], 0, v[2:3]
	v_lshl_add_u64 v[0:1], v[0:1], 0, s[36:37]
	s_and_saveexec_b64 s[8:9], vcc
	s_cbranch_execz .LBB0_418
	s_waitcnt vmcnt(63)
	v_lshlrev_b32_e32 v16, 16, v136
	s_waitcnt lgkmcnt(1)
	v_and_b32_e32 v17, 0xffff0000, v136
	v_mov_b32_e32 v4, v54
	s_waitcnt lgkmcnt(0)
	v_pk_mul_f32 v[4:5], v[4:5], v[16:17]
	s_nop 0
	v_cvt_pk_bf16_f32 v4, v4, v5
	global_store_dword v[0:1], v4, off
; __device__ __forceinline__ int crow(int r, int hi) { return (r & 3) + 8 * (r >> 2) + 4 * hi; }
; __device__ __forceinline__ unsigned cvtpk(float lo, float hi) { return pg8::cvt_pk_bf16(lo, hi); }
; __device__ __forceinline__ float bf2f(unsigned b) { return __uint_as_float(b << 16); }
; __device__ __forceinline__ void sb_block(const att::bf16* Qh, const att::bf16* Kh, const att::bf16* Vh, const bf16_t* Zs, bf16_t* UB, int head, int P0, char* lds) {
;     ...
; #pragma unroll
;     for (int r = 0; r < 16; ++r) { const int orow = qlo + crow(r, hi);
; #pragma unroll
;         for (int d0 = 0; d0 < 4; ++d0) { const float v = o[d0][r]; const float vn = __shfl_xor(v, 1);
;             if ((r32 & 1) == 0) { const size_t off = (size_t)orow * DM + head * 128 + d0 * 32 + r32; const unsigned zz = *(const unsigned*)(Zs + off);
;                 *(unsigned*)(UB + (size_t)orow * (2 * DM) + DM + head * 128 + d0 * 32 + r32) = cvtpk(v * bf2f(zz & 0xffffu), vn * bf2f(zz >> 16)); } } }
.LBB0_418:
	s_or_b64 exec, exec, s[8:9]
	s_waitcnt lgkmcnt(0)
	ds_bpermute_b32 v5, v74, v38
	s_and_saveexec_b64 s[8:9], vcc
	s_cbranch_execz .LBB0_420
	s_waitcnt vmcnt(63)
	v_lshlrev_b32_e32 v16, 16, v137
	v_and_b32_e32 v17, 0xffff0000, v137
	v_mov_b32_e32 v4, v38
	s_waitcnt lgkmcnt(0)
	v_pk_mul_f32 v[4:5], v[4:5], v[16:17]
	s_nop 0
	v_cvt_pk_bf16_f32 v4, v4, v5
	global_store_dword v[0:1], v4, off offset:64
.LBB0_420:
	s_or_b64 exec, exec, s[8:9]
	s_waitcnt lgkmcnt(0)
	ds_bpermute_b32 v5, v74, v22
	s_and_saveexec_b64 s[8:9], vcc
	s_cbranch_execz .LBB0_422
	s_waitcnt vmcnt(63)
	v_lshlrev_b32_e32 v16, 16, v138
	v_and_b32_e32 v17, 0xffff0000, v138
	v_mov_b32_e32 v4, v22
	s_waitcnt lgkmcnt(0)
	v_pk_mul_f32 v[4:5], v[4:5], v[16:17]
	s_nop 0
	v_cvt_pk_bf16_f32 v4, v4, v5
	global_store_dword v[0:1], v4, off offset:128
.LBB0_422:
	s_or_b64 exec, exec, s[8:9]
	s_waitcnt lgkmcnt(0)
	ds_bpermute_b32 v5, v74, v6
	s_and_saveexec_b64 s[8:9], vcc
	s_cbranch_execz .LBB0_424
	v_mov_b32_e32 v4, v6
	s_waitcnt vmcnt(63)
	v_lshlrev_b32_e32 v2, 16, v139
	v_and_b32_e32 v3, 0xffff0000, v139
	s_waitcnt lgkmcnt(0)
	v_pk_mul_f32 v[2:3], v[4:5], v[2:3]
	s_nop 0
	v_cvt_pk_bf16_f32 v2, v2, v3
	global_store_dword v[0:1], v2, off offset:192
.LBB0_424:
	s_or_b64 exec, exec, s[8:9]
	v_or_b32_e32 v0, 11, v64
	v_ashrrev_i32_e32 v1, 31, v0
	v_lshlrev_b64 v[2:3], 12, v[0:1]
	v_lshlrev_b64 v[0:1], 13, v[0:1]
	s_waitcnt lgkmcnt(0)
	ds_bpermute_b32 v5, v74, v55
	v_lshl_add_u64 v[0:1], s[6:7], 0, v[0:1]
	v_lshl_add_u64 v[0:1], v[0:1], 0, s[22:23]
	v_lshl_add_u64 v[0:1], v[0:1], 0, v[200:201]
	v_lshl_add_u64 v[2:3], v[66:67], 0, v[2:3]
	v_lshl_add_u64 v[0:1], v[0:1], 0, s[36:37]
	s_and_saveexec_b64 s[8:9], vcc
	s_cbranch_execz .LBB0_426
	s_waitcnt vmcnt(63)
	v_lshlrev_b32_e32 v16, 16, v140
	v_and_b32_e32 v17, 0xffff0000, v140
	v_mov_b32_e32 v4, v55
	s_waitcnt lgkmcnt(0)
	v_pk_mul_f32 v[4:5], v[4:5], v[16:17]
	s_nop 0
	v_cvt_pk_bf16_f32 v4, v4, v5
	global_store_dword v[0:1], v4, off
.LBB0_426:
	s_or_b64 exec, exec, s[8:9]
	s_waitcnt lgkmcnt(0)
	ds_bpermute_b32 v5, v74, v39
	s_and_saveexec_b64 s[8:9], vcc
	s_cbranch_execz .LBB0_428
	s_waitcnt vmcnt(63)
	v_lshlrev_b32_e32 v16, 16, v141
	v_and_b32_e32 v17, 0xffff0000, v141
	v_mov_b32_e32 v4, v39
	s_waitcnt lgkmcnt(0)
	v_pk_mul_f32 v[4:5], v[4:5], v[16:17]
	s_nop 0
	v_cvt_pk_bf16_f32 v4, v4, v5
	global_store_dword v[0:1], v4, off offset:64
.LBB0_428:
	s_or_b64 exec, exec, s[8:9]
	s_waitcnt lgkmcnt(0)
	ds_bpermute_b32 v5, v74, v23
	s_and_saveexec_b64 s[8:9], vcc
	s_cbranch_execz .LBB0_430
	s_waitcnt vmcnt(63)
	v_lshlrev_b32_e32 v16, 16, v142
	v_and_b32_e32 v17, 0xffff0000, v142
	v_mov_b32_e32 v4, v23
	s_waitcnt lgkmcnt(0)
	v_pk_mul_f32 v[4:5], v[4:5], v[16:17]
	s_nop 0
	v_cvt_pk_bf16_f32 v4, v4, v5
	global_store_dword v[0:1], v4, off offset:128
.LBB0_430:
	s_or_b64 exec, exec, s[8:9]
	s_waitcnt lgkmcnt(0)
	ds_bpermute_b32 v5, v74, v7
	s_and_saveexec_b64 s[8:9], vcc
	s_cbranch_execz .LBB0_432
	v_mov_b32_e32 v4, v7
	s_waitcnt vmcnt(63)
	v_lshlrev_b32_e32 v2, 16, v143
	v_and_b32_e32 v3, 0xffff0000, v143
	s_waitcnt lgkmcnt(0)
	v_pk_mul_f32 v[2:3], v[4:5], v[2:3]
	s_nop 0
	v_cvt_pk_bf16_f32 v2, v2, v3
	global_store_dword v[0:1], v2, off offset:192
.LBB0_432:
	s_or_b64 exec, exec, s[8:9]
	v_or_b32_e32 v0, 16, v64
	v_ashrrev_i32_e32 v1, 31, v0
	v_lshlrev_b64 v[2:3], 12, v[0:1]
	v_lshlrev_b64 v[0:1], 13, v[0:1]
	s_waitcnt lgkmcnt(0)
	ds_bpermute_b32 v5, v74, v56
	v_lshl_add_u64 v[0:1], s[6:7], 0, v[0:1]
	v_lshl_add_u64 v[0:1], v[0:1], 0, s[22:23]
	v_lshl_add_u64 v[0:1], v[0:1], 0, v[200:201]
	v_lshl_add_u64 v[2:3], v[66:67], 0, v[2:3]
	v_lshl_add_u64 v[0:1], v[0:1], 0, s[36:37]
	s_and_saveexec_b64 s[8:9], vcc
	s_cbranch_execz .LBB0_434
	s_waitcnt vmcnt(63)
	v_lshlrev_b32_e32 v6, 16, v144
	v_and_b32_e32 v7, 0xffff0000, v144
	v_mov_b32_e32 v4, v56
	s_waitcnt lgkmcnt(0)
	v_pk_mul_f32 v[4:5], v[4:5], v[6:7]
	s_nop 0
	v_cvt_pk_bf16_f32 v4, v4, v5
	global_store_dword v[0:1], v4, off
.LBB0_434:
	s_or_b64 exec, exec, s[8:9]
	s_waitcnt lgkmcnt(0)
	ds_bpermute_b32 v5, v74, v40
	s_and_saveexec_b64 s[8:9], vcc
	s_cbranch_execz .LBB0_436
	s_waitcnt vmcnt(63)
	v_lshlrev_b32_e32 v6, 16, v145
	v_and_b32_e32 v7, 0xffff0000, v145
	v_mov_b32_e32 v4, v40
	s_waitcnt lgkmcnt(0)
	v_pk_mul_f32 v[4:5], v[4:5], v[6:7]
	s_nop 0
	v_cvt_pk_bf16_f32 v4, v4, v5
	global_store_dword v[0:1], v4, off offset:64
.LBB0_436:
	s_or_b64 exec, exec, s[8:9]
	s_waitcnt lgkmcnt(0)
	ds_bpermute_b32 v5, v74, v24
	s_and_saveexec_b64 s[8:9], vcc
	s_cbranch_execz .LBB0_438
	s_waitcnt vmcnt(63)
	v_lshlrev_b32_e32 v6, 16, v146
	v_and_b32_e32 v7, 0xffff0000, v146
	v_mov_b32_e32 v4, v24
	s_waitcnt lgkmcnt(0)
	v_pk_mul_f32 v[4:5], v[4:5], v[6:7]
	s_nop 0
	v_cvt_pk_bf16_f32 v4, v4, v5
	global_store_dword v[0:1], v4, off offset:128
.LBB0_438:
	s_or_b64 exec, exec, s[8:9]
	s_waitcnt lgkmcnt(0)
	ds_bpermute_b32 v5, v74, v8
	s_and_saveexec_b64 s[8:9], vcc
	s_cbranch_execz .LBB0_440
	v_mov_b32_e32 v4, v8
	s_waitcnt vmcnt(63)
	v_lshlrev_b32_e32 v2, 16, v147
	v_and_b32_e32 v3, 0xffff0000, v147
	s_waitcnt lgkmcnt(0)
	v_pk_mul_f32 v[2:3], v[4:5], v[2:3]
	s_nop 0
	v_cvt_pk_bf16_f32 v2, v2, v3
	global_store_dword v[0:1], v2, off offset:192
.LBB0_440:
	s_or_b64 exec, exec, s[8:9]
	v_or_b32_e32 v0, 17, v64
	v_ashrrev_i32_e32 v1, 31, v0
	v_lshlrev_b64 v[2:3], 12, v[0:1]
	v_lshlrev_b64 v[0:1], 13, v[0:1]
	s_waitcnt lgkmcnt(0)
	ds_bpermute_b32 v5, v74, v57
	v_lshl_add_u64 v[0:1], s[6:7], 0, v[0:1]
	v_lshl_add_u64 v[0:1], v[0:1], 0, s[22:23]
	v_lshl_add_u64 v[0:1], v[0:1], 0, v[200:201]
	v_lshl_add_u64 v[2:3], v[66:67], 0, v[2:3]
	v_lshl_add_u64 v[0:1], v[0:1], 0, s[36:37]
	s_and_saveexec_b64 s[8:9], vcc
	s_cbranch_execz .LBB0_442
	s_waitcnt vmcnt(63)
	v_lshlrev_b32_e32 v6, 16, v148
	v_and_b32_e32 v7, 0xffff0000, v148
	v_mov_b32_e32 v4, v57
	s_waitcnt lgkmcnt(0)
	v_pk_mul_f32 v[4:5], v[4:5], v[6:7]
	s_nop 0
	v_cvt_pk_bf16_f32 v4, v4, v5
	global_store_dword v[0:1], v4, off
; __device__ __forceinline__ int crow(int r, int hi) { return (r & 3) + 8 * (r >> 2) + 4 * hi; }
; __device__ __forceinline__ unsigned cvtpk(float lo, float hi) { return pg8::cvt_pk_bf16(lo, hi); }
; __device__ __forceinline__ float bf2f(unsigned b) { return __uint_as_float(b << 16); }
; __device__ __forceinline__ void sb_block(const att::bf16* Qh, const att::bf16* Kh, const att::bf16* Vh, const bf16_t* Zs, bf16_t* UB, int head, int P0, char* lds) {
;     ...
; #pragma unroll
;     for (int r = 0; r < 16; ++r) { const int orow = qlo + crow(r, hi);
; #pragma unroll
;         for (int d0 = 0; d0 < 4; ++d0) { const float v = o[d0][r]; const float vn = __shfl_xor(v, 1);
;             if ((r32 & 1) == 0) { const size_t off = (size_t)orow * DM + head * 128 + d0 * 32 + r32; const unsigned zz = *(const unsigned*)(Zs + off);
;                 *(unsigned*)(UB + (size_t)orow * (2 * DM) + DM + head * 128 + d0 * 32 + r32) = cvtpk(v * bf2f(zz & 0xffffu), vn * bf2f(zz >> 16)); } } }
.LBB0_442:
	s_or_b64 exec, exec, s[8:9]
	s_waitcnt lgkmcnt(0)
	ds_bpermute_b32 v5, v74, v41
	s_and_saveexec_b64 s[8:9], vcc
	s_cbranch_execz .LBB0_444
	s_waitcnt vmcnt(63)
	v_lshlrev_b32_e32 v6, 16, v149
	v_and_b32_e32 v7, 0xffff0000, v149
	v_mov_b32_e32 v4, v41
	s_waitcnt lgkmcnt(0)
	v_pk_mul_f32 v[4:5], v[4:5], v[6:7]
	s_nop 0
	v_cvt_pk_bf16_f32 v4, v4, v5
	global_store_dword v[0:1], v4, off offset:64
.LBB0_444:
	s_or_b64 exec, exec, s[8:9]
	s_waitcnt lgkmcnt(0)
	ds_bpermute_b32 v5, v74, v25
	s_and_saveexec_b64 s[8:9], vcc
	s_cbranch_execz .LBB0_446
	s_waitcnt vmcnt(63)
	v_lshlrev_b32_e32 v6, 16, v150
	v_and_b32_e32 v7, 0xffff0000, v150
	v_mov_b32_e32 v4, v25
	s_waitcnt lgkmcnt(0)
	v_pk_mul_f32 v[4:5], v[4:5], v[6:7]
	s_nop 0
	v_cvt_pk_bf16_f32 v4, v4, v5
	global_store_dword v[0:1], v4, off offset:128
.LBB0_446:
	s_or_b64 exec, exec, s[8:9]
	s_waitcnt lgkmcnt(0)
	ds_bpermute_b32 v5, v74, v9
	s_and_saveexec_b64 s[8:9], vcc
	s_cbranch_execz .LBB0_448
	v_mov_b32_e32 v4, v9
	s_waitcnt vmcnt(63)
	v_lshlrev_b32_e32 v2, 16, v151
	v_and_b32_e32 v3, 0xffff0000, v151
	s_waitcnt lgkmcnt(0)
	v_pk_mul_f32 v[2:3], v[4:5], v[2:3]
	s_nop 0
	v_cvt_pk_bf16_f32 v2, v2, v3
	global_store_dword v[0:1], v2, off offset:192
.LBB0_448:
	s_or_b64 exec, exec, s[8:9]
	v_or_b32_e32 v0, 18, v64
	v_ashrrev_i32_e32 v1, 31, v0
	v_lshlrev_b64 v[2:3], 12, v[0:1]
	v_lshlrev_b64 v[0:1], 13, v[0:1]
	s_waitcnt lgkmcnt(0)
	ds_bpermute_b32 v5, v74, v58
	v_lshl_add_u64 v[0:1], s[6:7], 0, v[0:1]
	v_lshl_add_u64 v[0:1], v[0:1], 0, s[22:23]
	v_lshl_add_u64 v[0:1], v[0:1], 0, v[200:201]
	v_lshl_add_u64 v[2:3], v[66:67], 0, v[2:3]
	v_lshl_add_u64 v[0:1], v[0:1], 0, s[36:37]
	s_and_saveexec_b64 s[8:9], vcc
	s_cbranch_execz .LBB0_450
	s_waitcnt vmcnt(63)
	v_lshlrev_b32_e32 v6, 16, v152
	v_and_b32_e32 v7, 0xffff0000, v152
	v_mov_b32_e32 v4, v58
	s_waitcnt lgkmcnt(0)
	v_pk_mul_f32 v[4:5], v[4:5], v[6:7]
	s_nop 0
	v_cvt_pk_bf16_f32 v4, v4, v5
	global_store_dword v[0:1], v4, off
.LBB0_450:
	s_or_b64 exec, exec, s[8:9]
	s_waitcnt lgkmcnt(0)
	ds_bpermute_b32 v5, v74, v42
	s_and_saveexec_b64 s[8:9], vcc
	s_cbranch_execz .LBB0_452
	s_waitcnt vmcnt(63)
	v_lshlrev_b32_e32 v6, 16, v153
	v_and_b32_e32 v7, 0xffff0000, v153
	v_mov_b32_e32 v4, v42
	s_waitcnt lgkmcnt(0)
	v_pk_mul_f32 v[4:5], v[4:5], v[6:7]
	s_nop 0
	v_cvt_pk_bf16_f32 v4, v4, v5
	global_store_dword v[0:1], v4, off offset:64
.LBB0_452:
	s_or_b64 exec, exec, s[8:9]
	s_waitcnt lgkmcnt(0)
	ds_bpermute_b32 v5, v74, v26
	s_and_saveexec_b64 s[8:9], vcc
	s_cbranch_execz .LBB0_454
	s_waitcnt vmcnt(63)
	v_lshlrev_b32_e32 v6, 16, v154
	v_and_b32_e32 v7, 0xffff0000, v154
	v_mov_b32_e32 v4, v26
	s_waitcnt lgkmcnt(0)
	v_pk_mul_f32 v[4:5], v[4:5], v[6:7]
	s_nop 0
	v_cvt_pk_bf16_f32 v4, v4, v5
	global_store_dword v[0:1], v4, off offset:128
.LBB0_454:
	s_or_b64 exec, exec, s[8:9]
	s_waitcnt lgkmcnt(0)
	ds_bpermute_b32 v5, v74, v10
	s_and_saveexec_b64 s[8:9], vcc
	s_cbranch_execz .LBB0_456
	v_mov_b32_e32 v4, v10
	s_waitcnt vmcnt(63)
	v_lshlrev_b32_e32 v2, 16, v155
	v_and_b32_e32 v3, 0xffff0000, v155
	s_waitcnt lgkmcnt(0)
	v_pk_mul_f32 v[2:3], v[4:5], v[2:3]
	s_nop 0
	v_cvt_pk_bf16_f32 v2, v2, v3
	global_store_dword v[0:1], v2, off offset:192
.LBB0_456:
	s_or_b64 exec, exec, s[8:9]
	v_or_b32_e32 v0, 19, v64
	v_ashrrev_i32_e32 v1, 31, v0
	v_lshlrev_b64 v[2:3], 12, v[0:1]
	v_lshlrev_b64 v[0:1], 13, v[0:1]
	s_waitcnt lgkmcnt(0)
	ds_bpermute_b32 v5, v74, v59
	v_lshl_add_u64 v[0:1], s[6:7], 0, v[0:1]
	v_lshl_add_u64 v[0:1], v[0:1], 0, s[22:23]
	v_lshl_add_u64 v[0:1], v[0:1], 0, v[200:201]
	v_lshl_add_u64 v[2:3], v[66:67], 0, v[2:3]
	v_lshl_add_u64 v[0:1], v[0:1], 0, s[36:37]
	s_and_saveexec_b64 s[8:9], vcc
	s_cbranch_execz .LBB0_458
	s_waitcnt vmcnt(63)
	v_lshlrev_b32_e32 v6, 16, v156
	v_and_b32_e32 v7, 0xffff0000, v156
	v_mov_b32_e32 v4, v59
	s_waitcnt lgkmcnt(0)
	v_pk_mul_f32 v[4:5], v[4:5], v[6:7]
	s_nop 0
	v_cvt_pk_bf16_f32 v4, v4, v5
	global_store_dword v[0:1], v4, off
.LBB0_458:
	s_or_b64 exec, exec, s[8:9]
	s_waitcnt lgkmcnt(0)
	ds_bpermute_b32 v5, v74, v43
	s_and_saveexec_b64 s[8:9], vcc
	s_cbranch_execz .LBB0_460
	s_waitcnt vmcnt(63)
	v_lshlrev_b32_e32 v6, 16, v157
	v_and_b32_e32 v7, 0xffff0000, v157
	v_mov_b32_e32 v4, v43
	s_waitcnt lgkmcnt(0)
	v_pk_mul_f32 v[4:5], v[4:5], v[6:7]
	s_nop 0
	v_cvt_pk_bf16_f32 v4, v4, v5
	global_store_dword v[0:1], v4, off offset:64
.LBB0_460:
	s_or_b64 exec, exec, s[8:9]
	s_waitcnt lgkmcnt(0)
	ds_bpermute_b32 v5, v74, v27
	s_and_saveexec_b64 s[8:9], vcc
	s_cbranch_execz .LBB0_462
	s_waitcnt vmcnt(63)
	v_lshlrev_b32_e32 v6, 16, v158
	v_and_b32_e32 v7, 0xffff0000, v158
	v_mov_b32_e32 v4, v27
	s_waitcnt lgkmcnt(0)
	v_pk_mul_f32 v[4:5], v[4:5], v[6:7]
	s_nop 0
	v_cvt_pk_bf16_f32 v4, v4, v5
	global_store_dword v[0:1], v4, off offset:128
.LBB0_462:
	s_or_b64 exec, exec, s[8:9]
	s_waitcnt lgkmcnt(0)
	ds_bpermute_b32 v5, v74, v11
	s_and_saveexec_b64 s[8:9], vcc
	s_cbranch_execz .LBB0_464
	v_mov_b32_e32 v4, v11
	s_waitcnt vmcnt(63)
	v_lshlrev_b32_e32 v2, 16, v159
	v_and_b32_e32 v3, 0xffff0000, v159
	s_waitcnt lgkmcnt(0)
	v_pk_mul_f32 v[2:3], v[4:5], v[2:3]
	s_nop 0
	v_cvt_pk_bf16_f32 v2, v2, v3
	global_store_dword v[0:1], v2, off offset:192
.LBB0_464:
	s_or_b64 exec, exec, s[8:9]
	v_or_b32_e32 v0, 24, v64
	v_ashrrev_i32_e32 v1, 31, v0
	v_lshlrev_b64 v[2:3], 12, v[0:1]
	v_lshlrev_b64 v[0:1], 13, v[0:1]
	s_waitcnt lgkmcnt(0)
	ds_bpermute_b32 v5, v74, v60
	v_lshl_add_u64 v[0:1], s[6:7], 0, v[0:1]
	v_lshl_add_u64 v[0:1], v[0:1], 0, s[22:23]
	v_lshl_add_u64 v[0:1], v[0:1], 0, v[200:201]
	v_lshl_add_u64 v[2:3], v[66:67], 0, v[2:3]
	v_lshl_add_u64 v[0:1], v[0:1], 0, s[36:37]
	s_and_saveexec_b64 s[8:9], vcc
	s_cbranch_execz .LBB0_466
	s_waitcnt vmcnt(63)
	v_lshlrev_b32_e32 v6, 16, v160
	v_and_b32_e32 v7, 0xffff0000, v160
	v_mov_b32_e32 v4, v60
	s_waitcnt lgkmcnt(0)
	v_pk_mul_f32 v[4:5], v[4:5], v[6:7]
	s_nop 0
	v_cvt_pk_bf16_f32 v4, v4, v5
	global_store_dword v[0:1], v4, off
; __device__ __forceinline__ int crow(int r, int hi) { return (r & 3) + 8 * (r >> 2) + 4 * hi; }
; __device__ __forceinline__ unsigned cvtpk(float lo, float hi) { return pg8::cvt_pk_bf16(lo, hi); }
; __device__ __forceinline__ float bf2f(unsigned b) { return __uint_as_float(b << 16); }
; __device__ __forceinline__ void sb_block(const att::bf16* Qh, const att::bf16* Kh, const att::bf16* Vh, const bf16_t* Zs, bf16_t* UB, int head, int P0, char* lds) {
;     ...
; #pragma unroll
;     for (int r = 0; r < 16; ++r) { const int orow = qlo + crow(r, hi);
; #pragma unroll
;         for (int d0 = 0; d0 < 4; ++d0) { const float v = o[d0][r]; const float vn = __shfl_xor(v, 1);
;             if ((r32 & 1) == 0) { const size_t off = (size_t)orow * DM + head * 128 + d0 * 32 + r32; const unsigned zz = *(const unsigned*)(Zs + off);
;                 *(unsigned*)(UB + (size_t)orow * (2 * DM) + DM + head * 128 + d0 * 32 + r32) = cvtpk(v * bf2f(zz & 0xffffu), vn * bf2f(zz >> 16)); } } }
.LBB0_466:
	s_or_b64 exec, exec, s[8:9]
	s_waitcnt lgkmcnt(0)
	ds_bpermute_b32 v5, v74, v44
	s_and_saveexec_b64 s[8:9], vcc
	s_cbranch_execz .LBB0_468
	s_waitcnt vmcnt(63)
	v_lshlrev_b32_e32 v6, 16, v161
	v_and_b32_e32 v7, 0xffff0000, v161
	v_mov_b32_e32 v4, v44
	s_waitcnt lgkmcnt(0)
	v_pk_mul_f32 v[4:5], v[4:5], v[6:7]
	s_nop 0
	v_cvt_pk_bf16_f32 v4, v4, v5
	global_store_dword v[0:1], v4, off offset:64
.LBB0_468:
	s_or_b64 exec, exec, s[8:9]
	s_waitcnt lgkmcnt(0)
	ds_bpermute_b32 v5, v74, v28
	s_and_saveexec_b64 s[8:9], vcc
	s_cbranch_execz .LBB0_470
	s_waitcnt vmcnt(63)
	v_lshlrev_b32_e32 v6, 16, v162
	v_and_b32_e32 v7, 0xffff0000, v162
	v_mov_b32_e32 v4, v28
	s_waitcnt lgkmcnt(0)
	v_pk_mul_f32 v[4:5], v[4:5], v[6:7]
	s_nop 0
	v_cvt_pk_bf16_f32 v4, v4, v5
	global_store_dword v[0:1], v4, off offset:128
.LBB0_470:
	s_or_b64 exec, exec, s[8:9]
	s_waitcnt lgkmcnt(0)
	ds_bpermute_b32 v5, v74, v12
	s_and_saveexec_b64 s[8:9], vcc
	s_cbranch_execz .LBB0_472
	v_mov_b32_e32 v4, v12
	s_waitcnt vmcnt(63)
	v_lshlrev_b32_e32 v2, 16, v163
	v_and_b32_e32 v3, 0xffff0000, v163
	s_waitcnt lgkmcnt(0)
	v_pk_mul_f32 v[2:3], v[4:5], v[2:3]
	s_nop 0
	v_cvt_pk_bf16_f32 v2, v2, v3
	global_store_dword v[0:1], v2, off offset:192
.LBB0_472:
	s_or_b64 exec, exec, s[8:9]
	v_or_b32_e32 v0, 25, v64
	v_ashrrev_i32_e32 v1, 31, v0
	v_lshlrev_b64 v[2:3], 12, v[0:1]
	v_lshlrev_b64 v[0:1], 13, v[0:1]
	s_waitcnt lgkmcnt(0)
	ds_bpermute_b32 v5, v74, v61
	v_lshl_add_u64 v[0:1], s[6:7], 0, v[0:1]
	v_lshl_add_u64 v[0:1], v[0:1], 0, s[22:23]
	v_lshl_add_u64 v[0:1], v[0:1], 0, v[200:201]
	v_lshl_add_u64 v[2:3], v[66:67], 0, v[2:3]
	v_lshl_add_u64 v[0:1], v[0:1], 0, s[36:37]
	s_and_saveexec_b64 s[8:9], vcc
	s_cbranch_execz .LBB0_474
	s_waitcnt vmcnt(63)
	v_lshlrev_b32_e32 v6, 16, v164
	v_and_b32_e32 v7, 0xffff0000, v164
	v_mov_b32_e32 v4, v61
	s_waitcnt lgkmcnt(0)
	v_pk_mul_f32 v[4:5], v[4:5], v[6:7]
	s_nop 0
	v_cvt_pk_bf16_f32 v4, v4, v5
	global_store_dword v[0:1], v4, off
.LBB0_474:
	s_or_b64 exec, exec, s[8:9]
	s_waitcnt lgkmcnt(0)
	ds_bpermute_b32 v5, v74, v45
	s_and_saveexec_b64 s[8:9], vcc
	s_cbranch_execz .LBB0_476
	s_waitcnt vmcnt(63)
	v_lshlrev_b32_e32 v6, 16, v165
	v_and_b32_e32 v7, 0xffff0000, v165
	v_mov_b32_e32 v4, v45
	s_waitcnt lgkmcnt(0)
	v_pk_mul_f32 v[4:5], v[4:5], v[6:7]
	s_nop 0
	v_cvt_pk_bf16_f32 v4, v4, v5
	global_store_dword v[0:1], v4, off offset:64
.LBB0_476:
	s_or_b64 exec, exec, s[8:9]
	s_waitcnt lgkmcnt(0)
	ds_bpermute_b32 v5, v74, v29
	s_and_saveexec_b64 s[8:9], vcc
	s_cbranch_execz .LBB0_478
	s_waitcnt vmcnt(63)
	v_lshlrev_b32_e32 v6, 16, v166
	v_and_b32_e32 v7, 0xffff0000, v166
	v_mov_b32_e32 v4, v29
	s_waitcnt lgkmcnt(0)
	v_pk_mul_f32 v[4:5], v[4:5], v[6:7]
	s_nop 0
	v_cvt_pk_bf16_f32 v4, v4, v5
	global_store_dword v[0:1], v4, off offset:128
.LBB0_478:
	s_or_b64 exec, exec, s[8:9]
	s_waitcnt lgkmcnt(0)
	ds_bpermute_b32 v5, v74, v13
	s_and_saveexec_b64 s[8:9], vcc
	s_cbranch_execz .LBB0_480
	v_mov_b32_e32 v4, v13
	s_waitcnt vmcnt(63)
	v_lshlrev_b32_e32 v2, 16, v167
	v_and_b32_e32 v3, 0xffff0000, v167
	s_waitcnt lgkmcnt(0)
	v_pk_mul_f32 v[2:3], v[4:5], v[2:3]
	s_nop 0
	v_cvt_pk_bf16_f32 v2, v2, v3
	global_store_dword v[0:1], v2, off offset:192
.LBB0_480:
	s_or_b64 exec, exec, s[8:9]
	v_or_b32_e32 v0, 26, v64
	v_ashrrev_i32_e32 v1, 31, v0
	v_lshlrev_b64 v[2:3], 12, v[0:1]
	v_lshlrev_b64 v[0:1], 13, v[0:1]
	s_waitcnt lgkmcnt(0)
	ds_bpermute_b32 v5, v74, v62
	v_lshl_add_u64 v[0:1], s[6:7], 0, v[0:1]
	v_lshl_add_u64 v[0:1], v[0:1], 0, s[22:23]
	v_lshl_add_u64 v[0:1], v[0:1], 0, v[200:201]
	v_lshl_add_u64 v[2:3], v[66:67], 0, v[2:3]
	v_lshl_add_u64 v[0:1], v[0:1], 0, s[36:37]
	s_and_saveexec_b64 s[8:9], vcc
	s_cbranch_execz .LBB0_482
	s_waitcnt vmcnt(63)
	v_lshlrev_b32_e32 v6, 16, v168
	v_and_b32_e32 v7, 0xffff0000, v168
	v_mov_b32_e32 v4, v62
	s_waitcnt lgkmcnt(0)
	v_pk_mul_f32 v[4:5], v[4:5], v[6:7]
	s_nop 0
	v_cvt_pk_bf16_f32 v4, v4, v5
	global_store_dword v[0:1], v4, off
; __device__ __forceinline__ int crow(int r, int hi) { return (r & 3) + 8 * (r >> 2) + 4 * hi; }
; __device__ __forceinline__ unsigned cvtpk(float lo, float hi) { return pg8::cvt_pk_bf16(lo, hi); }
; __device__ __forceinline__ float bf2f(unsigned b) { return __uint_as_float(b << 16); }
; __device__ __forceinline__ void sb_block(const att::bf16* Qh, const att::bf16* Kh, const att::bf16* Vh, const bf16_t* Zs, bf16_t* UB, int head, int P0, char* lds) {
;     ...
; #pragma unroll
;     for (int r = 0; r < 16; ++r) { const int orow = qlo + crow(r, hi);
; #pragma unroll
;         for (int d0 = 0; d0 < 4; ++d0) { const float v = o[d0][r]; const float vn = __shfl_xor(v, 1);
;             if ((r32 & 1) == 0) { const size_t off = (size_t)orow * DM + head * 128 + d0 * 32 + r32; const unsigned zz = *(const unsigned*)(Zs + off);
;                 *(unsigned*)(UB + (size_t)orow * (2 * DM) + DM + head * 128 + d0 * 32 + r32) = cvtpk(v * bf2f(zz & 0xffffu), vn * bf2f(zz >> 16)); } } }
.LBB0_482:
	s_or_b64 exec, exec, s[8:9]
	s_waitcnt lgkmcnt(0)
	ds_bpermute_b32 v5, v74, v46
	s_and_saveexec_b64 s[8:9], vcc
	s_cbranch_execz .LBB0_484
	s_waitcnt vmcnt(63)
	v_lshlrev_b32_e32 v6, 16, v169
	v_and_b32_e32 v7, 0xffff0000, v169
	v_mov_b32_e32 v4, v46
	s_waitcnt lgkmcnt(0)
	v_pk_mul_f32 v[4:5], v[4:5], v[6:7]
	s_nop 0
	v_cvt_pk_bf16_f32 v4, v4, v5
	global_store_dword v[0:1], v4, off offset:64
.LBB0_484:
	s_or_b64 exec, exec, s[8:9]
	s_waitcnt lgkmcnt(0)
	ds_bpermute_b32 v5, v74, v30
	s_and_saveexec_b64 s[8:9], vcc
	s_cbranch_execz .LBB0_486
	s_waitcnt vmcnt(63)
	v_lshlrev_b32_e32 v6, 16, v170
	v_and_b32_e32 v7, 0xffff0000, v170
	v_mov_b32_e32 v4, v30
	s_waitcnt lgkmcnt(0)
	v_pk_mul_f32 v[4:5], v[4:5], v[6:7]
	s_nop 0
	v_cvt_pk_bf16_f32 v4, v4, v5
	global_store_dword v[0:1], v4, off offset:128
.LBB0_486:
	s_or_b64 exec, exec, s[8:9]
	s_waitcnt lgkmcnt(0)
	ds_bpermute_b32 v5, v74, v14
	s_and_saveexec_b64 s[8:9], vcc
	s_cbranch_execz .LBB0_488
	v_mov_b32_e32 v4, v14
	s_waitcnt vmcnt(63)
	v_lshlrev_b32_e32 v2, 16, v171
	v_and_b32_e32 v3, 0xffff0000, v171
	s_waitcnt lgkmcnt(0)
	v_pk_mul_f32 v[2:3], v[4:5], v[2:3]
	s_nop 0
	v_cvt_pk_bf16_f32 v2, v2, v3
	global_store_dword v[0:1], v2, off offset:192
.LBB0_488:
	s_or_b64 exec, exec, s[8:9]
	v_or_b32_e32 v2, 27, v64
	v_ashrrev_i32_e32 v3, 31, v2
	v_lshlrev_b64 v[0:1], 12, v[2:3]
	v_lshlrev_b64 v[2:3], 13, v[2:3]
	s_waitcnt lgkmcnt(0)
	ds_bpermute_b32 v5, v74, v63
	v_lshl_add_u64 v[2:3], s[6:7], 0, v[2:3]
	v_lshl_add_u64 v[2:3], v[2:3], 0, s[22:23]
	v_lshl_add_u64 v[2:3], v[2:3], 0, v[200:201]
	v_lshl_add_u64 v[0:1], v[66:67], 0, v[0:1]
	v_lshl_add_u64 v[2:3], v[2:3], 0, s[36:37]
	s_and_saveexec_b64 s[8:9], vcc
	s_cbranch_execz .LBB0_490
	s_waitcnt vmcnt(63)
	v_lshlrev_b32_e32 v6, 16, v172
	v_and_b32_e32 v7, 0xffff0000, v172
	v_mov_b32_e32 v4, v63
	s_waitcnt lgkmcnt(0)
	v_pk_mul_f32 v[4:5], v[4:5], v[6:7]
	s_nop 0
	v_cvt_pk_bf16_f32 v4, v4, v5
	global_store_dword v[2:3], v4, off
.LBB0_490:
	s_or_b64 exec, exec, s[8:9]
	s_waitcnt lgkmcnt(0)
	ds_bpermute_b32 v5, v74, v47
	s_and_saveexec_b64 s[8:9], vcc
	s_cbranch_execz .LBB0_492
	s_waitcnt vmcnt(63)
	v_lshlrev_b32_e32 v6, 16, v173
	v_and_b32_e32 v7, 0xffff0000, v173
	v_mov_b32_e32 v4, v47
	s_waitcnt lgkmcnt(0)
	v_pk_mul_f32 v[4:5], v[4:5], v[6:7]
	s_nop 0
	v_cvt_pk_bf16_f32 v4, v4, v5
	global_store_dword v[2:3], v4, off offset:64
.LBB0_492:
	s_or_b64 exec, exec, s[8:9]
	s_waitcnt lgkmcnt(0)
	ds_bpermute_b32 v5, v74, v31
	s_and_saveexec_b64 s[8:9], vcc
	s_cbranch_execz .LBB0_494
	s_waitcnt vmcnt(63)
	v_lshlrev_b32_e32 v6, 16, v174
	v_and_b32_e32 v7, 0xffff0000, v174
	v_mov_b32_e32 v4, v31
	s_waitcnt lgkmcnt(0)
	v_pk_mul_f32 v[4:5], v[4:5], v[6:7]
	s_nop 0
	v_cvt_pk_bf16_f32 v4, v4, v5
	global_store_dword v[2:3], v4, off offset:128
.LBB0_494:
	s_or_b64 exec, exec, s[8:9]
	s_waitcnt lgkmcnt(0)
	ds_bpermute_b32 v5, v74, v15
	s_and_saveexec_b64 s[8:9], vcc
	s_cbranch_execz .LBB0_361
	v_mov_b32_e32 v4, v15
	s_waitcnt vmcnt(63)
	v_lshlrev_b32_e32 v0, 16, v175
	v_and_b32_e32 v1, 0xffff0000, v175
	s_waitcnt lgkmcnt(0)
	v_pk_mul_f32 v[0:1], v[4:5], v[0:1]
	s_nop 0
	v_cvt_pk_bf16_f32 v0, v0, v1
	global_store_dword v[2:3], v0, off offset:192
	s_branch .LBB0_361

; __global__ void __launch_bounds__(NTHR, 2) fwd_mega(Params p) {
	.amdhsa_kernel _Z8fwd_mega6Params
		.amdhsa_group_segment_fixed_size 0
		.amdhsa_private_segment_fixed_size 0
		.amdhsa_kernarg_size 408
		.amdhsa_user_sgpr_count 2
		.amdhsa_user_sgpr_dispatch_ptr 0
		.amdhsa_user_sgpr_queue_ptr 0
		.amdhsa_user_sgpr_kernarg_segment_ptr 1
		.amdhsa_user_sgpr_dispatch_id 0
		.amdhsa_user_sgpr_kernarg_preload_length 0
		.amdhsa_user_sgpr_kernarg_preload_offset 0
		.amdhsa_user_sgpr_private_segment_size 0
		.amdhsa_uses_dynamic_stack 0
		.amdhsa_enable_private_segment 0
		.amdhsa_system_sgpr_workgroup_id_x 1
		.amdhsa_system_sgpr_workgroup_id_y 0
		.amdhsa_system_sgpr_workgroup_id_z 0
		.amdhsa_system_sgpr_workgroup_info 0
		.amdhsa_system_vgpr_workitem_id 2
		.amdhsa_next_free_vgpr 256
		.amdhsa_next_free_sgpr 102
		.amdhsa_accum_offset 256
		.amdhsa_reserve_vcc 1
		.amdhsa_float_round_mode_32 0
		.amdhsa_float_round_mode_16_64 0
		.amdhsa_float_denorm_mode_32 3
		.amdhsa_float_denorm_mode_16_64 3
		.amdhsa_dx10_clamp 1
		.amdhsa_ieee_mode 1
		.amdhsa_fp16_overflow 0
		.amdhsa_tg_split 0
		.amdhsa_exception_fp_ieee_invalid_op 0
		.amdhsa_exception_fp_denorm_src 0
		.amdhsa_exception_fp_ieee_div_zero 0
		.amdhsa_exception_fp_ieee_overflow 0
		.amdhsa_exception_fp_ieee_underflow 0
		.amdhsa_exception_fp_ieee_inexact 0
		.amdhsa_exception_int_div_zero 0
	.end_amdhsa_kernel
